# weight conversion of layers 1-3 moved from phase 0 into the idle tail of the previous layer G1 phase (192 workgroups without a last-round tile)
# speedup vs baseline: 1.0170x; 1.0034x over previous
; #define LAS __attribute__((address_space(3)))
; __device__ __forceinline__ unsigned xb_add(unsigned* p, unsigned v) { return __hip_atomic_fetch_add(p, v, __ATOMIC_RELAXED, __HIP_MEMORY_SCOPE_AGENT); }
; __device__ __forceinline__ unsigned xb_xcc_id() { return (unsigned)__builtin_amdgcn_s_getreg((3 << 11) | 20) & 0xFu; }
; __device__ __forceinline__ XcdBarrier xcd_barrier_post(unsigned* bar, volatile LAS unsigned* st) {
;     XcdBarrier b; b.bar = bar; b.x = xb_xcc_id(); b.st = st;
;     if (threadIdx.x == 0) (void)xb_add(&bar[XB_XCNT(b.x)], 1u);
;     return b;
; __global__ void __launch_bounds__(NTHR, 2) mega_fwd(Args args) {
;     extern __shared__ __attribute__((aligned(16))) unsigned char lds_raw[];
;     LAS unsigned char* lds = (LAS unsigned char*)lds_raw;
;     cg::grid_group grid = cg::this_grid();
;     volatile LAS unsigned* bst = (volatile LAS unsigned*)(lds + LDS_BYTES - 64);
;     if (threadIdx.x < 16) bst[threadIdx.x] = 0u;
;     __syncthreads();
;     XcdBarrier xbar = xcd_barrier_post((unsigned*)(args.ws + WS_BAR), bst);
_Z8mega_fwd4Args:
	s_load_dwordx8 s[24:31], s[0:1], 0xa0
	s_mov_b32 s100, 0
	s_movk_i32 s101, 0x40bf
	s_load_dwordx8 s[4:11], s[0:1], 0x80
	s_load_dwordx2 s[90:91], s[0:1], 0xc0
	s_mov_b32 s89, s2
	s_add_u32 s2, s0, 0xc0
	s_addc_u32 s3, s1, 0
	s_waitcnt lgkmcnt(0)
	v_writelane_b32 v251, s4, 0
	v_and_b32_e32 v141, 0x3ff, v0
	v_cmp_gt_u32_e32 vcc, 16, v141
	v_writelane_b32 v251, s5, 1
	v_writelane_b32 v251, s6, 2
	v_writelane_b32 v251, s7, 3
	v_writelane_b32 v251, s8, 4
	v_writelane_b32 v251, s9, 5
	v_writelane_b32 v251, s10, 6
	v_writelane_b32 v251, s11, 7
	v_writelane_b32 v251, s2, 8
	s_nop 1
	v_writelane_b32 v251, s3, 9
	s_and_saveexec_b64 s[2:3], vcc
	v_lshl_add_u32 v1, v141, 2, 0
	v_add_u32_e32 v1, 0x23fc0, v1
	v_mov_b32_e32 v2, 0
	ds_write_b32 v1, v2
	s_or_b64 exec, exec, s[2:3]
	s_waitcnt lgkmcnt(0)
	s_barrier
	s_add_u32 s2, s28, 0xc00000
	s_getreg_b32 s4, hwreg(HW_REG_XCC_ID, 0, 4)
	s_addc_u32 s3, s29, 0
	s_and_b32 s6, s4, 15
	v_cmp_eq_u32_e64 s[68:69], 0, v141
	s_and_saveexec_b64 s[4:5], s[68:69]
	s_cbranch_execz .LBB0_5
	s_mov_b64 s[8:9], exec
	v_mbcnt_lo_u32_b32 v1, s8, 0
	v_mbcnt_hi_u32_b32 v1, s9, v1
	v_cmp_eq_u32_e32 vcc, 0, v1
	s_and_b64 s[10:11], exec, vcc
	s_mov_b64 exec, s[10:11]
	s_cbranch_execz .LBB0_5
	s_lshl_b32 s7, s6, 8
	s_bcnt1_i32_b64 s8, s[8:9]
	v_mov_b32_e32 v1, s7
	v_mov_b32_e32 v2, s8
	global_atomic_add v1, v2, s[2:3] offset:1024

; __device__ __forceinline__ float fsig(float x) { return __builtin_amdgcn_rcpf(1.0f + __expf(-x)); }
; #define LAS __attribute__((address_space(3)))
; __device__ __forceinline__ void phase_convert(const Args& a, LAS unsigned char* lds) {
;     int tid_ = threadIdx.x; asm volatile("" : "+v"(tid_)); const int tid = tid_, lane = tid & 63, wave = __builtin_amdgcn_readfirstlane(tid >> 6);
;     LAS float* scr = (LAS float*)(lds + wave * 16384);
;     const int gw = blockIdx.x * NWAVES + wave, NGW = gridDim.x * NWAVES;
;     unsigned char* ws = a.ws;
;     float* MOD = (float*)(ws + WS_MOD);
;     for (int it = blockIdx.x; it < DEPTH * 96; it += gridDim.x) {
;         const int l = it / 96, ch = it % 96, j = ch * 64 + lane, i0 = wave * 256;
;         LAS float* red = (LAS float*)(lds + 131072);
; #pragma unroll
;         for (int b = 0; b < 4; ++b)
; #pragma unroll
;             for (int q = 0; q < 4; ++q) { const int ii = q * 64 + lane; const float cv = a.in[I_C][b * D + i0 + ii]; scr[b * 256 + ii] = cv * fsig(cv); }
.LBB0_458:
	s_waitcnt vmcnt(0)
	v_mov_b32_e32 v38, v141
	v_readlane_b32 s40, v251, 12
	v_readfirstlane_b32 s38, v38
	s_ashr_i32 s3, s38, 6
	s_lshl_b32 s0, s3, 14
	v_readlane_b32 s41, v251, 13
	v_and_b32_e32 v0, 63, v38
	s_andn2_b64 vcc, exec, s[40:41]
	s_add_i32 s2, s0, 0
	s_cbranch_vccnz .LBB0_465
	s_cmp_lg_u32 s100, 0
	s_cbranch_scc1 .LBB0_465
	s_lshl_b32 s42, s3, 8
	s_add_i32 s0, 0, 0x20000
	s_ashr_i32 s43, s42, 31
	s_lshl_b32 s44, s3, 10
	v_lshlrev_b32_e32 v2, 2, v0
	s_cmp_lt_i32 s3, 4
	v_add_u32_e32 v39, s0, v2
	s_cselect_b64 s[0:1], -1, 0
	s_and_b32 s38, s38, 0x3fffffc0
	v_lshl_add_u32 v40, s38, 2, v39
	v_add_u32_e32 v41, s2, v2
	v_or_b32_e32 v2, 64, v0
	v_or_b32_e32 v3, 0x80, v0
	v_or_b32_e32 v28, 0xc0, v0
	s_add_i32 s38, s42, 0x800
	v_or_b32_e32 v6, s38, v0
	v_or_b32_e32 v8, s38, v2
	v_or_b32_e32 v10, s38, v3
	v_or_b32_e32 v12, s38, v28
	s_add_i32 s38, s42, 0x1000
	v_or_b32_e32 v4, s42, v0
	v_or_b32_e32 v14, s38, v0
	v_or_b32_e32 v16, s38, v2
	v_or_b32_e32 v18, s38, v3
	v_or_b32_e32 v20, s38, v28
	s_add_i32 s38, s42, 0x1800
	v_ashrrev_i32_e32 v5, 31, v4
	v_or_b32_e32 v22, s38, v0
	v_or_b32_e32 v24, s38, v2
	v_or_b32_e32 v26, s38, v3
	v_or_b32_e32 v28, s38, v28
	s_waitcnt lgkmcnt(0)
	v_ashrrev_i32_e32 v7, 31, v6
	v_ashrrev_i32_e32 v9, 31, v8
	v_ashrrev_i32_e32 v11, 31, v10
	v_ashrrev_i32_e32 v13, 31, v12
	v_ashrrev_i32_e32 v15, 31, v14
	v_ashrrev_i32_e32 v17, 31, v16
	v_ashrrev_i32_e32 v19, 31, v18
	v_ashrrev_i32_e32 v21, 31, v20
	v_ashrrev_i32_e32 v23, 31, v22
	v_ashrrev_i32_e32 v25, 31, v24
	v_ashrrev_i32_e32 v27, 31, v26
	v_ashrrev_i32_e32 v29, 31, v28
	v_lshl_add_u64 v[2:3], v[4:5], 2, s[10:11]
	v_mov_b32_e32 v5, s43
	v_lshl_add_u64 v[4:5], v[4:5], 2, s[10:11]
	v_lshl_add_u64 v[6:7], v[6:7], 2, s[10:11]
	v_lshl_add_u64 v[8:9], v[8:9], 2, s[10:11]
	v_lshl_add_u64 v[10:11], v[10:11], 2, s[10:11]
	v_lshl_add_u64 v[12:13], v[12:13], 2, s[10:11]
	v_lshl_add_u64 v[14:15], v[14:15], 2, s[10:11]
	v_lshl_add_u64 v[16:17], v[16:17], 2, s[10:11]
	v_lshl_add_u64 v[18:19], v[18:19], 2, s[10:11]
	v_lshl_add_u64 v[20:21], v[20:21], 2, s[10:11]
	v_lshl_add_u64 v[22:23], v[22:23], 2, s[10:11]
	v_lshl_add_u64 v[24:25], v[24:25], 2, s[10:11]
	v_lshl_add_u64 v[26:27], v[26:27], 2, s[10:11]
	v_lshl_add_u64 v[28:29], v[28:29], 2, s[10:11]
	s_mov_b32 s45, s89
	s_branch .LBB0_461

; #define LAS __attribute__((address_space(3)))
; #define LDS_WAIT() asm volatile("s_waitcnt lgkmcnt(0)" ::: "memory")
;     ...
; #pragma unroll 8
;     for (int i = 0; i < 32; ++i) { const int kk = 2 * i + (lane >> 5); scr[kk * 33 + (lane & 31)] = W[(size_t)(k0 + kk) * N + n0 + (lane & 31)]; }
;     LDS_WAIT(); asm volatile("" ::: "memory");
;     const int c = lane & 7;
; #pragma unroll
;     for (int j = 0; j < 4; ++j) { const int n = (lane >> 3) + 8 * j; const LAS float* s = scr + (8 * c) * 33 + n;
; __device__ __forceinline__ void phase_convert(const Args& a, LAS unsigned char* lds) {
;     ...
;     for (int it = gw; it < DEPTH * I_L; it += NGW) {
;         const int l = it / I_L; int r = it % I_L;
;         if (r < I_IN) { transpose_item(a.in[I_WIN] + (size_t)l * D * NIN, D, NIN, (bf16*)(ws + WS_WIN + l * SZ_WIN), 3200, scr, r, lane); continue; } r -= I_IN;
.LBB0_465:
	v_readlane_b32 s0, v251, 11
	s_add_i32 s42, s3, s0
	s_cmp_lg_u32 s100, 0
	s_cselect_b32 s1, 0x200, 0
	s_sub_i32 s1, s101, s1
	s_sub_i32 s1, s1, 0x40bf
	s_add_i32 s42, s42, s1
	s_cmp_gt_i32 s42, s101
	s_cbranch_scc1 .LBB0_500
	v_lshrrev_b32_e32 v2, 5, v0
	s_waitcnt lgkmcnt(0)
	v_lshrrev_b32_e32 v7, 3, v0
	v_lshlrev_b32_e32 v0, 3, v0
	v_and_b32_e32 v8, 56, v0
	v_readlane_b32 s0, v251, 14
	v_lshlrev_b32_e32 v0, 1, v8
	v_readlane_b32 s1, v251, 15
	v_and_b32_e32 v4, 31, v38
	v_mul_u32_u24_e32 v3, 0x84, v8
	v_lshl_add_u64 v[10:11], s[0:1], 0, v[0:1]
	v_readlane_b32 s0, v251, 16
	v_lshlrev_b32_e32 v5, 2, v7
	v_readlane_b32 s1, v251, 17
	v_lshl_add_u32 v6, v4, 2, s2
	v_add3_u32 v9, s2, v3, v5
	v_or_b32_e32 v18, 8, v7
	v_or_b32_e32 v19, 16, v7
	v_or_b32_e32 v20, 24, v7
	v_lshl_add_u64 v[12:13], s[0:1], 0, v[0:1]
	v_mov_b32_e32 v3, v2
	s_branch .LBB0_468
.LBB0_467:
	s_cmp_lg_u32 s100, 0
	s_cselect_b32 s0, 0x600, s94
	s_add_i32 s42, s42, s0
	s_cmp_gt_i32 s42, s101
	s_cbranch_scc1 .LBB0_500

; __global__ void __launch_bounds__(NTHR, 2) mega_fwd(Args args) {
;     ...
;     for (int ph = args.lo; ph < args.hi; ++ph) {
;         unsigned char* ws = args.ws; asm volatile("" : "+s"(ws));
;         if (ph == 0) {
;     ...
;         if (args.hi < 0) grid.sync();
;         if (ph + 1 < args.hi) { xcd_barrier(xbar);
;     ...
;             xcd_barrier(xbar);
;     ...
;         }
;     }
.LBB0_507:
	v_readlane_b32 s0, v252, 53
	v_readlane_b32 s1, v252, 54
	s_andn2_b64 vcc, exec, s[0:1]
	v_readlane_b32 s2, v253, 59
	v_readlane_b32 s3, v253, 60
	s_cbranch_vccz .LBB0_509
	s_cmp_lg_u32 s100, 0
	s_cbranch_scc1 .Lconv_ret
	s_lshr_b32 s0, 0x4104, s30
	s_and_b32 s0, s0, 1
	s_cbranch_scc0 .Lconv_none
	s_cmpk_lt_u32 s89, 64
	s_cbranch_scc1 .Lconv_none
	s_cmpk_lg_u32 s90, 0x100
	s_cbranch_scc1 .Lconv_none
	s_add_i32 s100, s30, 1
	s_add_i32 s101, s30, 4
	s_mulk_i32 s101, 43
	s_lshr_b32 s101, s101, 8
	s_mulk_i32 s101, 0x40c0
	s_addk_i32 s101, 0x40bf
	s_mov_b32 s30, 0
	s_branch .LBB0_10
.Lconv_ret:
	s_add_i32 s30, s100, -1
	s_mov_b32 s100, 0
	s_movk_i32 s101, 0x40bf
.Lconv_none:
	s_add_i32 s30, s30, 1
	s_cmp_ge_i32 s30, s31
	s_mov_b64 s[0:1], -1
	s_cbranch_scc1 .LBB0_9
	s_branch .LBB0_520
